# v85 + one static s_setprio 1 for waves 0-3 (the waves with the extra output MFMA/convert/store work per step) in the GDN and GLA scan loops, reset at scan exit
# baseline (speedup 1.0000x reference)
; #define LAS __attribute__((address_space(3)))
; __device__ __forceinline__ void gdn_scan_wg(const Ctx& F, int hv, int sl) {
;     const Params& P = *F.p;
;     LAS bf16_t* Sb = (LAS bf16_t*)F.lds;
;     const int lane = F.lane, w = F.wave, fr = lane & 15, fq = lane >> 4, dv0 = sl * 16;
;     const bf16_t* Pg = WSP(bf16_t, WS_H); const bf16_t* RTg = WSP(bf16_t, WS_RAW + 64 * MiB);
;     const bf16_t* QEg = WSP(bf16_t, WS_BIG + B_QE); const bf16_t* OUg = WSP(bf16_t, WS_BIG + B_OU);
;     const float* GG = WSP(float, WS_SMALL + SM_GG); bf16_t* O = WSP(bf16_t, WS_RAW);
;     for (int e = F.tid; e < 2 * 16 * 136; e += 512) Sb[e] = 0;
;     f32x4 s = (f32x4){0.f, 0.f, 0.f, 0.f};
;     int* prog = WSP(int, WS_SMALL + SM_PROG) + hv * 64; const bool publish = (sl == 0);
;     constexpr int RS = 4;
;     GS ring[RS];
; #pragma unroll
;     for (int i = 0; i < RS - 1; ++i) gs_load(ring[i], Pg, RTg, QEg, OUg, GG, hv, i, w, fr, fq, dv0);
;     asm volatile("s_waitcnt lgkmcnt(0)" ::: "memory"); __builtin_amdgcn_s_barrier(); asm volatile("" ::: "memory");
.LBB0_947:
.LBB0_948:
	s_add_u32 s6, s92, s13
	s_addc_u32 s9, s93, 0
	s_add_u32 s8, s6, 0x520000
	s_addc_u32 s9, s9, 0
	s_cmp_lt_u32 s2, 8
	s_movk_i32 s6, 0x110
	s_cselect_b64 s[26:27], -1, 0
	v_mad_u32_u24 v213, v56, s6, 0
	s_lshl_b32 s6, s22, 3
	s_add_i32 s12, s6, s12
	v_lshl_or_b32 v164, s94, 4, v56
	v_mov_b32_e32 v165, 0
	s_mov_b32 s15, s7
	s_or_b32 s24, s13, 3
	s_ashr_i32 s13, s12, 31
	v_lshl_add_u64 v[184:185], v[48:49], 1, s[14:15]
	v_add_u32_e32 v48, 0x2c0, v164
	v_mov_b32_e32 v49, v165
	v_and_b32_e32 v215, 48, v212
	s_lshl_b64 s[20:21], s[12:13], 19
	v_lshlrev_b64 v[48:49], 5, v[48:49]
	v_lshlrev_b64 v[52:53], 1, v[52:53]
	v_lshrrev_b32_e32 v56, 1, v215
	v_lshl_add_u64 v[48:49], s[20:21], 0, v[48:49]
	v_lshl_add_u64 v[160:161], s[16:17], 0, v[52:53]
	s_mov_b64 s[16:17], 0xac00000
	v_or_b32_e32 v48, v48, v56
	v_lshl_add_u64 v[186:187], v[48:49], 0, s[16:17]
	v_add_u32_e32 v48, 0x280, v164
	v_mov_b32_e32 v49, v165
	v_lshlrev_b64 v[48:49], 5, v[48:49]
	v_lshl_add_u64 v[48:49], s[20:21], 0, v[48:49]
	v_or_b32_e32 v48, v48, v56
	v_lshl_add_u64 v[188:189], v[48:49], 0, s[16:17]
	v_add_u32_e32 v48, 0x240, v164
	v_mov_b32_e32 v49, v165
	v_lshlrev_b64 v[48:49], 5, v[48:49]
	v_lshl_add_u64 v[48:49], s[20:21], 0, v[48:49]
	v_or_b32_e32 v48, v48, v56
	v_lshl_add_u64 v[190:191], v[48:49], 0, s[16:17]
	v_add_u32_e32 v48, 0x200, v164
	v_mov_b32_e32 v49, v165
	v_lshlrev_b64 v[48:49], 5, v[48:49]
	v_lshl_add_u64 v[48:49], s[20:21], 0, v[48:49]
	v_or_b32_e32 v48, v48, v56
	v_lshl_add_u64 v[192:193], v[48:49], 0, s[16:17]
	v_add_u32_e32 v48, 0x1c0, v164
	v_mov_b32_e32 v49, v165
	v_lshlrev_b64 v[48:49], 5, v[48:49]
	v_lshl_add_u64 v[48:49], s[20:21], 0, v[48:49]
	v_or_b32_e32 v48, v48, v56
	v_lshl_add_u64 v[194:195], v[48:49], 0, s[16:17]
	v_add_u32_e32 v48, 0x180, v164
	v_mov_b32_e32 v49, v165
	v_lshlrev_b64 v[48:49], 5, v[48:49]
	v_lshl_add_u64 v[162:163], v[54:55], 1, s[18:19]
	v_lshlrev_b64 v[54:55], 5, v[164:165]
	v_lshl_add_u64 v[48:49], s[20:21], 0, v[48:49]
	v_lshl_add_u64 v[54:55], s[20:21], 0, v[54:55]
	v_or_b32_e32 v48, v48, v56
	v_or_b32_e32 v54, v54, v56
	v_lshl_add_u64 v[196:197], v[48:49], 0, s[16:17]
	v_add_u32_e32 v48, 0x140, v164
	v_mov_b32_e32 v49, v165
	v_lshl_add_u64 v[166:167], v[54:55], 0, s[16:17]
	v_add_u32_e32 v54, 0x3c0, v164
	v_mov_b32_e32 v55, v165
	v_lshlrev_b64 v[48:49], 5, v[48:49]
	v_lshlrev_b64 v[54:55], 5, v[54:55]
	v_lshl_add_u64 v[48:49], s[20:21], 0, v[48:49]
	v_lshl_add_u64 v[54:55], s[20:21], 0, v[54:55]
	v_or_b32_e32 v48, v48, v56
	v_or_b32_e32 v54, v54, v56
	v_lshl_add_u64 v[198:199], v[48:49], 0, s[16:17]
	v_add_u32_e32 v48, 0x100, v164
	v_mov_b32_e32 v49, v165
	v_lshl_add_u64 v[170:171], v[54:55], 0, s[16:17]
	v_add_u32_e32 v54, 0x380, v164
	v_mov_b32_e32 v55, v165
	v_lshlrev_b64 v[48:49], 5, v[48:49]
	v_lshlrev_b64 v[54:55], 5, v[54:55]
	v_lshl_add_u64 v[48:49], s[20:21], 0, v[48:49]
	v_lshl_add_u64 v[54:55], s[20:21], 0, v[54:55]
	v_or_b32_e32 v48, v48, v56
	v_or_b32_e32 v54, v54, v56
	v_lshl_add_u64 v[200:201], v[48:49], 0, s[16:17]
	v_add_u32_e32 v48, 0xc0, v164
	v_mov_b32_e32 v49, v165
	v_lshl_add_u64 v[172:173], v[54:55], 0, s[16:17]
	v_add_u32_e32 v54, 0x340, v164
	v_mov_b32_e32 v55, v165
	v_lshlrev_b64 v[48:49], 5, v[48:49]
	v_lshlrev_b64 v[54:55], 5, v[54:55]
	v_lshl_add_u64 v[48:49], s[20:21], 0, v[48:49]
	v_lshl_add_u64 v[54:55], s[20:21], 0, v[54:55]
	v_or_b32_e32 v48, v48, v56
	v_or_b32_e32 v54, v54, v56
	v_lshl_add_u64 v[202:203], v[48:49], 0, s[16:17]
	v_add_u32_e32 v48, 0x80, v164
	v_mov_b32_e32 v49, v165
	v_lshl_add_u64 v[174:175], v[54:55], 0, s[16:17]
	v_add_u32_e32 v54, 0x300, v164
	v_mov_b32_e32 v55, v165
	v_lshlrev_b64 v[48:49], 5, v[48:49]
	v_lshlrev_b64 v[54:55], 5, v[54:55]
	v_lshl_add_u64 v[48:49], s[20:21], 0, v[48:49]
	v_lshl_add_u64 v[54:55], s[20:21], 0, v[54:55]
	v_or_b32_e32 v48, v48, v56
	v_add_u32_e32 v164, 64, v164
	v_or_b32_e32 v54, v54, v56
	v_lshl_add_u64 v[204:205], v[48:49], 0, s[16:17]
	v_lshlrev_b64 v[48:49], 5, v[164:165]
	s_waitcnt lgkmcnt(0)
	s_barrier
	v_lshl_add_u64 v[176:177], v[54:55], 0, s[16:17]
	v_add_u32_e32 v54, s23, v57
	v_lshl_add_u64 v[48:49], s[20:21], 0, v[48:49]
	v_lshl_add_u32 v59, s94, 5, v213
	v_lshlrev_b32_e32 v58, 3, v58
	v_cmp_eq_u32_e32 vcc, 0, v212
	s_lshl_b32 s6, s22, 22
	v_ashrrev_i32_e32 v55, 31, v54
	v_or_b32_e32 v48, v48, v56
	s_mov_b32 s25, 0
	s_and_b64 s[12:13], vcc, s[26:27]
	s_mov_b32 s26, s7
	v_lshl_add_u64 v[178:179], v[54:55], 1, s[6:7]
	v_lshl_add_u64 v[180:181], v[50:51], 1, s[6:7]
	v_lshl_add_u64 v[182:183], s[14:15], 0, v[52:53]
	v_lshl_add_u64 v[206:207], v[48:49], 0, s[16:17]
	s_mov_b32 s27, 0x6c18000
	v_mov_b32_e32 v227, 0x510000
	s_mov_b32 s28, 0xffff0000
	s_movk_i32 s29, 0x7fff
	s_mov_b32 s30, 0x6c20000
	s_mov_b32 s31, 0x6c28000
	s_mov_b32 s34, 0x6c30000
	s_mov_b32 s35, 0x6c38000
	s_mov_b32 s38, 0x6c40000
	s_mov_b32 s39, 0x6c48000
	s_mov_b32 s40, 0x6c50000
	s_mov_b32 s41, 0x6c58000
	s_mov_b32 s44, 0x6c60000
	s_mov_b32 s45, 0x6c68000
	s_mov_b32 s52, 0x6c70000
	s_mov_b32 s53, 0x6c78000
	s_mov_b64 s[14:15], 0x8000
	s_mov_b64 s[16:17], 0x40000
	s_mov_b64 s[18:19], 0x80000
	v_add_u32_e32 v240, v59, v58
	v_mov_b32_e32 v138, 0
	v_mov_b32_e32 v139, v165
	v_mov_b32_e32 v136, 0
	v_mov_b32_e32 v137, v165
	s_and_b64 vcc, exec, s[0:1]
	s_cbranch_vccnz .Lgdn_prio_skip
	s_setprio 1
.Lgdn_prio_skip:
	s_branch .LBB0_950

; __device__ __forceinline__ void gdn_scan_wg(const Ctx& F, int hv, int sl) {
;     ...
;     asm volatile("s_waitcnt vmcnt(0)" ::: "memory");
.LBB0_1046:
	s_setprio 0
	s_waitcnt vmcnt(0)

; #define LAS __attribute__((address_space(3)))
; __device__ __forceinline__ void gla_scan_wg(const Ctx& F, int h, int sl) {
;     const Params& P = *F.p;
;     LAS float* OP = (LAS float*)F.lds;
;     const int tid = F.tid, lane = F.lane, w = F.wave, fr = lane & 15, fq = lane >> 4, dv0 = sl * 16, dk0 = w * 32;
;     const bf16_t* QT = WSP(bf16_t, WS_H); const bf16_t* KDTb = WSP(bf16_t, WS_H + 32 * MiB);
;     const bf16_t* ATTb = WSP(bf16_t, WS_BIG + B_ATT); const bf16_t* VTb = WSP(bf16_t, WS_BIG + B_VT);
;     const float* GLAST = WSP(float, WS_SMALL + SM_GLAST); bf16_t* O = WSP(bf16_t, WS_RAW);
;     f32x4 s0 = (f32x4){0.f, 0.f, 0.f, 0.f}, s1 = s0;
;     int* prog = WSP(int, WS_SMALL + SM_PROG) + (8 + (F.bid & 7)) * 64; const bool publish = (sl < 2);
;     LS ring[3];
;     ls_load(ring[0], QT, KDTb, ATTb, VTb, GLAST, h, 0, w, fr, fq, dv0, dk0);
;     ls_load(ring[1], QT, KDTb, ATTb, VTb, GLAST, h, 1, w, fr, fq, dv0, dk0);
.LBB0_1735:
	s_lshl_b32 s4, s76, 8
	s_and_b32 s4, s4, 0x700
	s_add_u32 s4, s92, s4
	s_addc_u32 s5, s93, 0
	s_add_u32 s16, s4, 0x520800
	s_addc_u32 s17, s5, 0
	s_cmp_lt_i32 s6, 2
	s_cselect_b64 s[4:5], -1, 0
	v_cmp_eq_u32_e32 vcc, 0, v212
	s_and_b64 s[18:19], vcc, s[4:5]
	s_lshl_b32 s4, s28, 5
	s_add_i32 s4, s4, s6
	s_ashr_i32 s5, s4, 31
	s_lshl_b64 s[30:31], s[4:5], 19
	v_readlane_b32 s4, v247, 0
	s_cmp_lt_u32 s4, 64
	s_cselect_b64 s[4:5], -1, 0
	s_cmp_eq_u32 s94, 1
	s_cselect_b64 s[6:7], -1, 0
	s_cmp_eq_u32 s94, 2
	s_cselect_b64 s[8:9], -1, 0
	s_cmp_eq_u32 s94, 3
	s_mov_b32 s15, 0
	s_cselect_b64 s[10:11], -1, 0
	s_lshl_b32 s25, s94, 12
	v_and_b32_e32 v101, 48, v212
	s_add_i32 s25, s25, 0
	s_mov_b32 s95, s15
	v_add_u32_e32 v102, s25, v101
	v_lshl_add_u64 v[222:223], s[12:13], 0, v[80:81]
	v_lshl_add_u64 v[224:225], s[20:21], 0, v[80:81]
	v_lshlrev_b64 v[82:83], 1, v[82:83]
	v_lshl_add_u64 v[230:231], s[14:15], 0, v[80:81]
	s_mov_b32 s25, s15
	s_lshl_b32 s14, s28, 21
	s_lshl_b64 s[12:13], s[94:95], 7
	v_mov_b32_e32 v80, 0
	v_lshl_add_u64 v[226:227], s[22:23], 0, v[82:83]
	v_lshl_add_u64 v[232:233], s[24:25], 0, v[82:83]
	s_add_u32 s12, s29, s12
	v_mov_b32_e32 v82, v80
	v_mov_b32_e32 v83, v80
	v_lshlrev_b32_e32 v100, 6, v100
	s_addc_u32 s13, 0, s13
	v_or_b32_e32 v238, s12, v101
	v_mov_b32_e32 v81, v80
	v_cndmask_b32_e64 v101, 0, 1, s[26:27]
	v_mov_b64_e32 v[110:111], v[82:83]
	v_mov_b64_e32 v[114:115], v[82:83]
	v_lshl_add_u32 v213, v212, 3, 0
	v_lshl_or_b32 v228, v212, 2, s30
	v_mov_b32_e32 v229, s31
	v_lshl_add_u64 v[234:235], v[218:219], 1, s[14:15]
	v_lshl_add_u64 v[236:237], v[220:221], 1, s[14:15]
	v_mov_b32_e32 v239, s13
	s_mov_b32 s38, 0x6c10000
	s_mov_b32 s39, 0x8c10000
	v_cmp_ne_u32_e64 s[12:13], 1, v101
	s_movk_i32 s40, 0x7fff
	s_mov_b32 s41, 0xffff0000
	s_mov_b32 s42, 0xac00000
	s_mov_b32 s43, 0x6c18000
	s_mov_b32 s44, 0x8c18000
	s_mov_b32 s45, 0xac01000
	s_mov_b64 s[20:21], 0x6000
	s_mov_b64 s[22:23], 0x60000
	s_mov_b64 s[24:25], 0xc0000
	s_mov_b64 s[26:27], 0x18000
	s_mov_b64 s[28:29], 0xc000
	v_add_u32_e32 v215, v102, v100
	v_mov_b32_e32 v243, 1
	v_mov_b64_e32 v[108:109], v[80:81]
	v_mov_b64_e32 v[112:113], v[80:81]
	s_mov_b32 s46, 0
	s_and_b64 vcc, exec, s[12:13]
	s_cbranch_vccnz .Lgla_prio_skip
	s_setprio 1
